# MLP-up GEMM epilogue regenerated by script: loads batched, permlane16/32-swap butterflies instead of ds_bpermute round trips, bare v_rsq, packed fma/mul, running 64-bit store pointer (486 instr vs 755
# speedup vs baseline: 1.0138x; 1.0044x over previous
; __device__ __forceinline__ unsigned cvt_pk_bf16(float lo, float hi) { unsigned r; asm volatile("v_cvt_pk_bf16_f32 %0, %1, %2" : "=v"(r) : "v"(lo), "v"(hi)); return r; }
;     __device__ __forceinline__ void operator()(const f32x4 (&acc)[2][2][4][2], const Unit& u, int wr, int wc, int fr, int fq) const {
;         const int rowt = u.pm * BM, b = rowt >= MLAT ? 2 : (rowt >> 13);
;         const int row0 = rowt + wr * 64 + fr, col0 = u.pn * BM + wc * 32 + 8 * fq;
;         f32x4 bv[2][2];
; #pragma unroll
;         for (int bj = 0; bj < 2; ++bj)
; #pragma unroll
;             for (int n = 0; n < 2; ++n) bv[bj][n] = *(const f32x4*)(bias + (size_t)b * nbias + col0 + bj * HALF + 4 * n);
;         float rsv[2][4];
;         { f32x4 pq[2][4];
; #pragma unroll
;           for (int ai = 0; ai < 2; ++ai)
; #pragma unroll
;               for (int m = 0; m < 4; ++m) pq[ai][m] = *(const f32x4*)(ssq + (size_t)(row0 + ai * HALF + m * 16) * 16 + 4 * fq);
; #pragma unroll
;           for (int ai = 0; ai < 2; ++ai)
; #pragma unroll
;               for (int m = 0; m < 4; ++m) { float t = (pq[ai][m][0] + pq[ai][m][1]) + (pq[ai][m][2] + pq[ai][m][3]); t += __shfl_xor(t, 16); t += __shfl_xor(t, 32);
;                   rsv[ai][m] = rsqrtf(t * (1.f / DM) + EPS); } }
; #pragma unroll
;         for (int ai = 0; ai < 2; ++ai)
; #pragma unroll
;             for (int m = 0; m < 4; ++m) { const int row = row0 + ai * HALF + m * 16; bf16_t* rowp = O + (size_t)row * ldc + col0; float s = 0.f, q = 0.f;
;                 const float rstd = rsv[ai][m];
; #pragma unroll
;                 for (int bj = 0; bj < 2; ++bj) { f32x4 v0 = acc[ai][bj][m][0] * rstd + bv[bj][0], v1 = acc[ai][bj][m][1] * rstd + bv[bj][1];
;                     if (ACT == 1) {
; #pragma unroll
;                         for (int e = 0; e < 4; ++e) { const float a = fmaxf(v0[e], 0.f), b2 = fmaxf(v1[e], 0.f); v0[e] = a * a; v1[e] = b2 * b2; } }
;                     if (ACT == 2) {
; #pragma unroll
;                         for (int e = 0; e < 4; ++e) { v0[e] = gelu_tanh(v0[e]); v1[e] = gelu_tanh(v1[e]); s += v0[e] + v1[e]; q += v0[e] * v0[e] + v1[e] * v1[e]; } }
;                     u32x4 w; w.x = cvt_pk_bf16(v0[0], v0[1]); w.y = cvt_pk_bf16(v0[2], v0[3]); w.z = cvt_pk_bf16(v1[0], v1[1]); w.w = cvt_pk_bf16(v1[2], v1[3]);
;                     *(u32x4*)(rowp + bj * HALF) = w; }
.LBB0_1696:
	s_min_i32 s16, s40, 64
	s_ashr_i32 s16, s16, 5
	s_lshl_b32 s16, s16, 14
	s_add_u32 s44, s63, s16
	s_addc_u32 s45, s64, 0
	v_lshl_add_u32 v196, s40, 8, v201
	v_lshl_or_b32 v192, s41, 8, v205
	v_mov_b32_e32 v197, 0
	v_lshlrev_b32_e32 v193, 2, v192
	v_lshlrev_b64 v[188:189], 6, v[196:197]
	v_lshl_add_u64 v[188:189], v[188:189], 0, v[174:175]
	global_load_dwordx4 v[128:131], v193, s[44:45] offset:0
	global_load_dwordx4 v[132:135], v193, s[44:45] offset:16
	global_load_dwordx4 v[136:139], v193, s[44:45] offset:512
	global_load_dwordx4 v[140:143], v193, s[44:45] offset:528
	s_mov_b64 s[40:41], 0x2000
	v_lshl_add_u64 v[194:195], v[188:189], 0, s[40:41]
	global_load_dwordx4 v[144:147], v[188:189], off offset:0
	global_load_dwordx4 v[148:151], v[188:189], off offset:1024
	global_load_dwordx4 v[152:155], v[188:189], off offset:2048
	global_load_dwordx4 v[156:159], v[188:189], off offset:3072
	global_load_dwordx4 v[160:163], v[194:195], off offset:0
	global_load_dwordx4 v[164:167], v[194:195], off offset:1024
	global_load_dwordx4 v[180:183], v[194:195], off offset:2048
	global_load_dwordx4 v[184:187], v[194:195], off offset:3072
	v_lshlrev_b32_e32 v190, 1, v192
	v_mov_b32_e32 v191, 0
	v_lshlrev_b64 v[208:209], 13, v[196:197]
	v_lshl_add_u64 v[208:209], v[208:209], 0, v[190:191]
	v_lshl_add_u64 v[208:209], s[14:15], 0, v[208:209]
	s_mov_b64 s[44:45], 0x20000
	s_waitcnt vmcnt(0)
	v_add_f32_e32 v144, v144, v145
	v_add_f32_e32 v146, v146, v147
	v_add_f32_e32 v148, v148, v149
	v_add_f32_e32 v150, v150, v151
	v_add_f32_e32 v152, v152, v153
	v_add_f32_e32 v154, v154, v155
	v_add_f32_e32 v156, v156, v157
	v_add_f32_e32 v158, v158, v159
	v_add_f32_e32 v160, v160, v161
	v_add_f32_e32 v162, v162, v163
	v_add_f32_e32 v164, v164, v165
	v_add_f32_e32 v166, v166, v167
	v_add_f32_e32 v180, v180, v181
	v_add_f32_e32 v182, v182, v183
	v_add_f32_e32 v184, v184, v185
	v_add_f32_e32 v186, v186, v187
	v_add_f32_e32 v216, v144, v146
	v_add_f32_e32 v217, v148, v150
	v_add_f32_e32 v218, v152, v154
	v_add_f32_e32 v219, v156, v158
	v_add_f32_e32 v220, v160, v162
	v_add_f32_e32 v221, v164, v166
	v_add_f32_e32 v222, v180, v182
	v_add_f32_e32 v223, v184, v186
	v_mov_b32_e32 v144, v216
	v_mov_b32_e32 v145, v216
	v_mov_b32_e32 v148, v217
	v_mov_b32_e32 v149, v217
	v_mov_b32_e32 v152, v218
	v_mov_b32_e32 v153, v218
	v_mov_b32_e32 v156, v219
	v_mov_b32_e32 v157, v219
	v_mov_b32_e32 v160, v220
	v_mov_b32_e32 v161, v220
	v_mov_b32_e32 v164, v221
	v_mov_b32_e32 v165, v221
	v_mov_b32_e32 v180, v222
	v_mov_b32_e32 v181, v222
	v_mov_b32_e32 v184, v223
	v_mov_b32_e32 v185, v223
	s_nop 1
	v_permlane16_swap_b32_e32 v144, v145
	v_permlane16_swap_b32_e32 v148, v149
	v_permlane16_swap_b32_e32 v152, v153
	v_permlane16_swap_b32_e32 v156, v157
	v_permlane16_swap_b32_e32 v160, v161
	v_permlane16_swap_b32_e32 v164, v165
	v_permlane16_swap_b32_e32 v180, v181
	v_permlane16_swap_b32_e32 v184, v185
	v_add_f32_e32 v216, v144, v145
	v_add_f32_e32 v217, v148, v149
	v_add_f32_e32 v218, v152, v153
	v_add_f32_e32 v219, v156, v157
	v_add_f32_e32 v220, v160, v161
	v_add_f32_e32 v221, v164, v165
	v_add_f32_e32 v222, v180, v181
	v_add_f32_e32 v223, v184, v185
	v_mov_b32_e32 v144, v216
	v_mov_b32_e32 v145, v216
	v_mov_b32_e32 v148, v217
	v_mov_b32_e32 v149, v217
	v_mov_b32_e32 v152, v218
	v_mov_b32_e32 v153, v218
	v_mov_b32_e32 v156, v219
	v_mov_b32_e32 v157, v219
	v_mov_b32_e32 v160, v220
	v_mov_b32_e32 v161, v220
	v_mov_b32_e32 v164, v221
	v_mov_b32_e32 v165, v221
	v_mov_b32_e32 v180, v222
	v_mov_b32_e32 v181, v222
	v_mov_b32_e32 v184, v223
	v_mov_b32_e32 v185, v223
	s_nop 1
	v_permlane32_swap_b32_e32 v144, v145
	v_permlane32_swap_b32_e32 v148, v149
	v_permlane32_swap_b32_e32 v152, v153
	v_permlane32_swap_b32_e32 v156, v157
	v_permlane32_swap_b32_e32 v160, v161
	v_permlane32_swap_b32_e32 v164, v165
	v_permlane32_swap_b32_e32 v180, v181
	v_permlane32_swap_b32_e32 v184, v185
	v_add_f32_e32 v216, v144, v145
	v_add_f32_e32 v217, v148, v149
	v_add_f32_e32 v218, v152, v153
	v_add_f32_e32 v219, v156, v157
	v_add_f32_e32 v220, v160, v161
	v_add_f32_e32 v221, v164, v165
	v_add_f32_e32 v222, v180, v181
	v_add_f32_e32 v223, v184, v185
	v_mov_b32_e32 v190, 0x358637bd
	v_fmamk_f32 v216, v216, 0x3a800000, v190
	v_fmamk_f32 v217, v217, 0x3a800000, v190
	v_fmamk_f32 v218, v218, 0x3a800000, v190
	v_fmamk_f32 v219, v219, 0x3a800000, v190
	v_fmamk_f32 v220, v220, 0x3a800000, v190
	v_fmamk_f32 v221, v221, 0x3a800000, v190
	v_fmamk_f32 v222, v222, 0x3a800000, v190
	v_fmamk_f32 v223, v223, 0x3a800000, v190
	v_rsq_f32_e32 v144, v216
	v_rsq_f32_e32 v146, v217
	v_rsq_f32_e32 v148, v218
	v_rsq_f32_e32 v150, v219
	v_rsq_f32_e32 v152, v220
	v_rsq_f32_e32 v154, v221
	v_rsq_f32_e32 v156, v222
	v_rsq_f32_e32 v158, v223
	s_nop 0
	v_pk_fma_f32 v[124:125], v[124:125], v[144:145], v[128:129] op_sel_hi:[1,0,1]
	v_pk_fma_f32 v[126:127], v[126:127], v[144:145], v[130:131] op_sel_hi:[1,0,1]
	v_pk_fma_f32 v[120:121], v[120:121], v[144:145], v[132:133] op_sel_hi:[1,0,1]
	v_pk_fma_f32 v[122:123], v[122:123], v[144:145], v[134:135] op_sel_hi:[1,0,1]
	v_max_f32_e32 v124, 0, v124
	v_max_f32_e32 v125, 0, v125
	v_max_f32_e32 v126, 0, v126
	v_max_f32_e32 v127, 0, v127
	v_max_f32_e32 v120, 0, v120
	v_max_f32_e32 v121, 0, v121
	v_max_f32_e32 v122, 0, v122
	v_max_f32_e32 v123, 0, v123
	v_pk_mul_f32 v[124:125], v[124:125], v[124:125]
	v_pk_mul_f32 v[126:127], v[126:127], v[126:127]
	v_pk_mul_f32 v[120:121], v[120:121], v[120:121]
	v_pk_mul_f32 v[122:123], v[122:123], v[122:123]
	v_cvt_pk_bf16_f32 v160, v124, v125
	v_cvt_pk_bf16_f32 v161, v126, v127
	v_cvt_pk_bf16_f32 v162, v120, v121
	v_cvt_pk_bf16_f32 v163, v122, v123
; __device__ __forceinline__ unsigned cvt_pk_bf16(float lo, float hi) { unsigned r; asm volatile("v_cvt_pk_bf16_f32 %0, %1, %2" : "=v"(r) : "v"(lo), "v"(hi)); return r; }
;     __device__ __forceinline__ void operator()(const f32x4 (&acc)[2][2][4][2], const Unit& u, int wr, int wc, int fr, int fq) const {
;     ...
;         for (int ai = 0; ai < 2; ++ai)
; #pragma unroll
;             for (int m = 0; m < 4; ++m) { const int row = row0 + ai * HALF + m * 16; bf16_t* rowp = O + (size_t)row * ldc + col0; float s = 0.f, q = 0.f;
;                 const float rstd = rsv[ai][m];
; #pragma unroll
;                 for (int bj = 0; bj < 2; ++bj) { f32x4 v0 = acc[ai][bj][m][0] * rstd + bv[bj][0], v1 = acc[ai][bj][m][1] * rstd + bv[bj][1];
;                     if (ACT == 1) {
; #pragma unroll
;                         for (int e = 0; e < 4; ++e) { const float a = fmaxf(v0[e], 0.f), b2 = fmaxf(v1[e], 0.f); v0[e] = a * a; v1[e] = b2 * b2; } }
;                     if (ACT == 2) {
; #pragma unroll
;                         for (int e = 0; e < 4; ++e) { v0[e] = gelu_tanh(v0[e]); v1[e] = gelu_tanh(v1[e]); s += v0[e] + v1[e]; q += v0[e] * v0[e] + v1[e] * v1[e]; } }
;                     u32x4 w; w.x = cvt_pk_bf16(v0[0], v0[1]); w.y = cvt_pk_bf16(v0[2], v0[3]); w.z = cvt_pk_bf16(v1[0], v1[1]); w.w = cvt_pk_bf16(v1[2], v1[3]);
;                     *(u32x4*)(rowp + bj * HALF) = w; }
	global_store_dwordx4 v[208:209], v[160:163], off sc1
	v_pk_fma_f32 v[116:117], v[116:117], v[144:145], v[136:137] op_sel_hi:[1,0,1]
	v_pk_fma_f32 v[118:119], v[118:119], v[144:145], v[138:139] op_sel_hi:[1,0,1]
	v_pk_fma_f32 v[112:113], v[112:113], v[144:145], v[140:141] op_sel_hi:[1,0,1]
	v_pk_fma_f32 v[114:115], v[114:115], v[144:145], v[142:143] op_sel_hi:[1,0,1]
	v_max_f32_e32 v116, 0, v116
	v_max_f32_e32 v117, 0, v117
	v_max_f32_e32 v118, 0, v118
	v_max_f32_e32 v119, 0, v119
	v_max_f32_e32 v112, 0, v112
	v_max_f32_e32 v113, 0, v113
	v_max_f32_e32 v114, 0, v114
	v_max_f32_e32 v115, 0, v115
	v_pk_mul_f32 v[116:117], v[116:117], v[116:117]
	v_pk_mul_f32 v[118:119], v[118:119], v[118:119]
	v_pk_mul_f32 v[112:113], v[112:113], v[112:113]
	v_pk_mul_f32 v[114:115], v[114:115], v[114:115]
	v_cvt_pk_bf16_f32 v164, v116, v117
	v_cvt_pk_bf16_f32 v165, v118, v119
	v_cvt_pk_bf16_f32 v166, v112, v113
	v_cvt_pk_bf16_f32 v167, v114, v115
	global_store_dwordx4 v[208:209], v[164:167], off offset:256 sc1
	v_pk_fma_f32 v[108:109], v[108:109], v[146:147], v[128:129] op_sel_hi:[1,0,1]
	v_pk_fma_f32 v[110:111], v[110:111], v[146:147], v[130:131] op_sel_hi:[1,0,1]
	v_pk_fma_f32 v[104:105], v[104:105], v[146:147], v[132:133] op_sel_hi:[1,0,1]
	v_pk_fma_f32 v[106:107], v[106:107], v[146:147], v[134:135] op_sel_hi:[1,0,1]
	v_lshl_add_u64 v[208:209], v[208:209], 0, s[44:45]
	v_max_f32_e32 v108, 0, v108
	v_max_f32_e32 v109, 0, v109
	v_max_f32_e32 v110, 0, v110
	v_max_f32_e32 v111, 0, v111
	v_max_f32_e32 v104, 0, v104
	v_max_f32_e32 v105, 0, v105
	v_max_f32_e32 v106, 0, v106
	v_max_f32_e32 v107, 0, v107
	v_pk_mul_f32 v[108:109], v[108:109], v[108:109]
	v_pk_mul_f32 v[110:111], v[110:111], v[110:111]
	v_pk_mul_f32 v[104:105], v[104:105], v[104:105]
	v_pk_mul_f32 v[106:107], v[106:107], v[106:107]
	v_cvt_pk_bf16_f32 v160, v108, v109
	v_cvt_pk_bf16_f32 v161, v110, v111
	v_cvt_pk_bf16_f32 v162, v104, v105
	v_cvt_pk_bf16_f32 v163, v106, v107
	global_store_dwordx4 v[208:209], v[160:163], off sc1
	v_pk_fma_f32 v[100:101], v[100:101], v[146:147], v[136:137] op_sel_hi:[1,0,1]
	v_pk_fma_f32 v[102:103], v[102:103], v[146:147], v[138:139] op_sel_hi:[1,0,1]
	v_pk_fma_f32 v[96:97], v[96:97], v[146:147], v[140:141] op_sel_hi:[1,0,1]
	v_pk_fma_f32 v[98:99], v[98:99], v[146:147], v[142:143] op_sel_hi:[1,0,1]
	v_max_f32_e32 v100, 0, v100
	v_max_f32_e32 v101, 0, v101
	v_max_f32_e32 v102, 0, v102
	v_max_f32_e32 v103, 0, v103
	v_max_f32_e32 v96, 0, v96
	v_max_f32_e32 v97, 0, v97
	v_max_f32_e32 v98, 0, v98
	v_max_f32_e32 v99, 0, v99
	v_pk_mul_f32 v[100:101], v[100:101], v[100:101]
	v_pk_mul_f32 v[102:103], v[102:103], v[102:103]
	v_pk_mul_f32 v[96:97], v[96:97], v[96:97]
	v_pk_mul_f32 v[98:99], v[98:99], v[98:99]
	v_cvt_pk_bf16_f32 v164, v100, v101
	v_cvt_pk_bf16_f32 v165, v102, v103
	v_cvt_pk_bf16_f32 v166, v96, v97
	v_cvt_pk_bf16_f32 v167, v98, v99
	global_store_dwordx4 v[208:209], v[164:167], off offset:256 sc1
	v_pk_fma_f32 v[92:93], v[92:93], v[148:149], v[128:129] op_sel_hi:[1,0,1]
	v_pk_fma_f32 v[94:95], v[94:95], v[148:149], v[130:131] op_sel_hi:[1,0,1]
	v_pk_fma_f32 v[88:89], v[88:89], v[148:149], v[132:133] op_sel_hi:[1,0,1]
	v_pk_fma_f32 v[90:91], v[90:91], v[148:149], v[134:135] op_sel_hi:[1,0,1]
	v_lshl_add_u64 v[208:209], v[208:209], 0, s[44:45]
	v_max_f32_e32 v92, 0, v92
	v_max_f32_e32 v93, 0, v93
	v_max_f32_e32 v94, 0, v94
	v_max_f32_e32 v95, 0, v95
	v_max_f32_e32 v88, 0, v88
	v_max_f32_e32 v89, 0, v89
	v_max_f32_e32 v90, 0, v90
	v_max_f32_e32 v91, 0, v91
	v_pk_mul_f32 v[92:93], v[92:93], v[92:93]
	v_pk_mul_f32 v[94:95], v[94:95], v[94:95]
	v_pk_mul_f32 v[88:89], v[88:89], v[88:89]
	v_pk_mul_f32 v[90:91], v[90:91], v[90:91]
	v_cvt_pk_bf16_f32 v160, v92, v93
	v_cvt_pk_bf16_f32 v161, v94, v95
	v_cvt_pk_bf16_f32 v162, v88, v89
	v_cvt_pk_bf16_f32 v163, v90, v91
	global_store_dwordx4 v[208:209], v[160:163], off sc1
	v_pk_fma_f32 v[84:85], v[84:85], v[148:149], v[136:137] op_sel_hi:[1,0,1]
	v_pk_fma_f32 v[86:87], v[86:87], v[148:149], v[138:139] op_sel_hi:[1,0,1]
	v_pk_fma_f32 v[80:81], v[80:81], v[148:149], v[140:141] op_sel_hi:[1,0,1]
	v_pk_fma_f32 v[82:83], v[82:83], v[148:149], v[142:143] op_sel_hi:[1,0,1]
	v_max_f32_e32 v84, 0, v84
	v_max_f32_e32 v85, 0, v85
	v_max_f32_e32 v86, 0, v86
	v_max_f32_e32 v87, 0, v87
	v_max_f32_e32 v80, 0, v80
	v_max_f32_e32 v81, 0, v81
	v_max_f32_e32 v82, 0, v82
	v_max_f32_e32 v83, 0, v83
	v_pk_mul_f32 v[84:85], v[84:85], v[84:85]
	v_pk_mul_f32 v[86:87], v[86:87], v[86:87]
	v_pk_mul_f32 v[80:81], v[80:81], v[80:81]
	v_pk_mul_f32 v[82:83], v[82:83], v[82:83]
	v_cvt_pk_bf16_f32 v164, v84, v85
	v_cvt_pk_bf16_f32 v165, v86, v87
	v_cvt_pk_bf16_f32 v166, v80, v81
	v_cvt_pk_bf16_f32 v167, v82, v83
	global_store_dwordx4 v[208:209], v[164:167], off offset:256 sc1
	v_pk_fma_f32 v[76:77], v[76:77], v[150:151], v[128:129] op_sel_hi:[1,0,1]
	v_pk_fma_f32 v[78:79], v[78:79], v[150:151], v[130:131] op_sel_hi:[1,0,1]
	v_pk_fma_f32 v[72:73], v[72:73], v[150:151], v[132:133] op_sel_hi:[1,0,1]
	v_pk_fma_f32 v[74:75], v[74:75], v[150:151], v[134:135] op_sel_hi:[1,0,1]
	v_lshl_add_u64 v[208:209], v[208:209], 0, s[44:45]
	v_max_f32_e32 v76, 0, v76
	v_max_f32_e32 v77, 0, v77
	v_max_f32_e32 v78, 0, v78
	v_max_f32_e32 v79, 0, v79
	v_max_f32_e32 v72, 0, v72
	v_max_f32_e32 v73, 0, v73
	v_max_f32_e32 v74, 0, v74
	v_max_f32_e32 v75, 0, v75
	v_pk_mul_f32 v[76:77], v[76:77], v[76:77]
	v_pk_mul_f32 v[78:79], v[78:79], v[78:79]
	v_pk_mul_f32 v[72:73], v[72:73], v[72:73]
	v_pk_mul_f32 v[74:75], v[74:75], v[74:75]
	v_cvt_pk_bf16_f32 v160, v76, v77
	v_cvt_pk_bf16_f32 v161, v78, v79
	v_cvt_pk_bf16_f32 v162, v72, v73
	v_cvt_pk_bf16_f32 v163, v74, v75
; __device__ __forceinline__ unsigned cvt_pk_bf16(float lo, float hi) { unsigned r; asm volatile("v_cvt_pk_bf16_f32 %0, %1, %2" : "=v"(r) : "v"(lo), "v"(hi)); return r; }
;     __device__ __forceinline__ void operator()(const f32x4 (&acc)[2][2][4][2], const Unit& u, int wr, int wc, int fr, int fq) const {
;     ...
;         for (int ai = 0; ai < 2; ++ai)
; #pragma unroll
;             for (int m = 0; m < 4; ++m) { const int row = row0 + ai * HALF + m * 16; bf16_t* rowp = O + (size_t)row * ldc + col0; float s = 0.f, q = 0.f;
;                 const float rstd = rsv[ai][m];
; #pragma unroll
;                 for (int bj = 0; bj < 2; ++bj) { f32x4 v0 = acc[ai][bj][m][0] * rstd + bv[bj][0], v1 = acc[ai][bj][m][1] * rstd + bv[bj][1];
;                     if (ACT == 1) {
; #pragma unroll
;                         for (int e = 0; e < 4; ++e) { const float a = fmaxf(v0[e], 0.f), b2 = fmaxf(v1[e], 0.f); v0[e] = a * a; v1[e] = b2 * b2; } }
;                     if (ACT == 2) {
; #pragma unroll
;                         for (int e = 0; e < 4; ++e) { v0[e] = gelu_tanh(v0[e]); v1[e] = gelu_tanh(v1[e]); s += v0[e] + v1[e]; q += v0[e] * v0[e] + v1[e] * v1[e]; } }
;                     u32x4 w; w.x = cvt_pk_bf16(v0[0], v0[1]); w.y = cvt_pk_bf16(v0[2], v0[3]); w.z = cvt_pk_bf16(v1[0], v1[1]); w.w = cvt_pk_bf16(v1[2], v1[3]);
;                     *(u32x4*)(rowp + bj * HALF) = w; }
	global_store_dwordx4 v[208:209], v[160:163], off sc1
	v_pk_fma_f32 v[68:69], v[68:69], v[150:151], v[136:137] op_sel_hi:[1,0,1]
	v_pk_fma_f32 v[70:71], v[70:71], v[150:151], v[138:139] op_sel_hi:[1,0,1]
	v_pk_fma_f32 v[64:65], v[64:65], v[150:151], v[140:141] op_sel_hi:[1,0,1]
	v_pk_fma_f32 v[66:67], v[66:67], v[150:151], v[142:143] op_sel_hi:[1,0,1]
	v_max_f32_e32 v68, 0, v68
	v_max_f32_e32 v69, 0, v69
	v_max_f32_e32 v70, 0, v70
	v_max_f32_e32 v71, 0, v71
	v_max_f32_e32 v64, 0, v64
	v_max_f32_e32 v65, 0, v65
	v_max_f32_e32 v66, 0, v66
	v_max_f32_e32 v67, 0, v67
	v_pk_mul_f32 v[68:69], v[68:69], v[68:69]
	v_pk_mul_f32 v[70:71], v[70:71], v[70:71]
	v_pk_mul_f32 v[64:65], v[64:65], v[64:65]
	v_pk_mul_f32 v[66:67], v[66:67], v[66:67]
	v_cvt_pk_bf16_f32 v164, v68, v69
	v_cvt_pk_bf16_f32 v165, v70, v71
	v_cvt_pk_bf16_f32 v166, v64, v65
	v_cvt_pk_bf16_f32 v167, v66, v67
	global_store_dwordx4 v[208:209], v[164:167], off offset:256 sc1
	v_pk_fma_f32 v[60:61], v[60:61], v[152:153], v[128:129] op_sel_hi:[1,0,1]
	v_pk_fma_f32 v[62:63], v[62:63], v[152:153], v[130:131] op_sel_hi:[1,0,1]
	v_pk_fma_f32 v[56:57], v[56:57], v[152:153], v[132:133] op_sel_hi:[1,0,1]
	v_pk_fma_f32 v[58:59], v[58:59], v[152:153], v[134:135] op_sel_hi:[1,0,1]
	s_mov_b64 s[40:41], 0xa0000
	v_lshl_add_u64 v[208:209], v[208:209], 0, s[40:41]
	v_max_f32_e32 v60, 0, v60
	v_max_f32_e32 v61, 0, v61
	v_max_f32_e32 v62, 0, v62
	v_max_f32_e32 v63, 0, v63
	v_max_f32_e32 v56, 0, v56
	v_max_f32_e32 v57, 0, v57
	v_max_f32_e32 v58, 0, v58
	v_max_f32_e32 v59, 0, v59
	v_pk_mul_f32 v[60:61], v[60:61], v[60:61]
	v_pk_mul_f32 v[62:63], v[62:63], v[62:63]
	v_pk_mul_f32 v[56:57], v[56:57], v[56:57]
	v_pk_mul_f32 v[58:59], v[58:59], v[58:59]
	v_cvt_pk_bf16_f32 v160, v60, v61
	v_cvt_pk_bf16_f32 v161, v62, v63
	v_cvt_pk_bf16_f32 v162, v56, v57
	v_cvt_pk_bf16_f32 v163, v58, v59
	global_store_dwordx4 v[208:209], v[160:163], off sc1
	v_pk_fma_f32 v[52:53], v[52:53], v[152:153], v[136:137] op_sel_hi:[1,0,1]
	v_pk_fma_f32 v[54:55], v[54:55], v[152:153], v[138:139] op_sel_hi:[1,0,1]
	v_pk_fma_f32 v[48:49], v[48:49], v[152:153], v[140:141] op_sel_hi:[1,0,1]
	v_pk_fma_f32 v[50:51], v[50:51], v[152:153], v[142:143] op_sel_hi:[1,0,1]
	v_max_f32_e32 v52, 0, v52
	v_max_f32_e32 v53, 0, v53
	v_max_f32_e32 v54, 0, v54
	v_max_f32_e32 v55, 0, v55
	v_max_f32_e32 v48, 0, v48
	v_max_f32_e32 v49, 0, v49
	v_max_f32_e32 v50, 0, v50
	v_max_f32_e32 v51, 0, v51
	v_pk_mul_f32 v[52:53], v[52:53], v[52:53]
	v_pk_mul_f32 v[54:55], v[54:55], v[54:55]
	v_pk_mul_f32 v[48:49], v[48:49], v[48:49]
	v_pk_mul_f32 v[50:51], v[50:51], v[50:51]
	v_cvt_pk_bf16_f32 v164, v52, v53
	v_cvt_pk_bf16_f32 v165, v54, v55
	v_cvt_pk_bf16_f32 v166, v48, v49
	v_cvt_pk_bf16_f32 v167, v50, v51
	global_store_dwordx4 v[208:209], v[164:167], off offset:256 sc1
	v_pk_fma_f32 v[44:45], v[44:45], v[154:155], v[128:129] op_sel_hi:[1,0,1]
	v_pk_fma_f32 v[46:47], v[46:47], v[154:155], v[130:131] op_sel_hi:[1,0,1]
	v_pk_fma_f32 v[40:41], v[40:41], v[154:155], v[132:133] op_sel_hi:[1,0,1]
	v_pk_fma_f32 v[42:43], v[42:43], v[154:155], v[134:135] op_sel_hi:[1,0,1]
	v_lshl_add_u64 v[208:209], v[208:209], 0, s[44:45]
	v_max_f32_e32 v44, 0, v44
	v_max_f32_e32 v45, 0, v45
	v_max_f32_e32 v46, 0, v46
	v_max_f32_e32 v47, 0, v47
	v_max_f32_e32 v40, 0, v40
	v_max_f32_e32 v41, 0, v41
	v_max_f32_e32 v42, 0, v42
	v_max_f32_e32 v43, 0, v43
	v_pk_mul_f32 v[44:45], v[44:45], v[44:45]
	v_pk_mul_f32 v[46:47], v[46:47], v[46:47]
	v_pk_mul_f32 v[40:41], v[40:41], v[40:41]
	v_pk_mul_f32 v[42:43], v[42:43], v[42:43]
	v_cvt_pk_bf16_f32 v160, v44, v45
	v_cvt_pk_bf16_f32 v161, v46, v47
	v_cvt_pk_bf16_f32 v162, v40, v41
	v_cvt_pk_bf16_f32 v163, v42, v43
	global_store_dwordx4 v[208:209], v[160:163], off sc1
	v_pk_fma_f32 v[36:37], v[36:37], v[154:155], v[136:137] op_sel_hi:[1,0,1]
	v_pk_fma_f32 v[38:39], v[38:39], v[154:155], v[138:139] op_sel_hi:[1,0,1]
	v_pk_fma_f32 v[32:33], v[32:33], v[154:155], v[140:141] op_sel_hi:[1,0,1]
	v_pk_fma_f32 v[34:35], v[34:35], v[154:155], v[142:143] op_sel_hi:[1,0,1]
	v_max_f32_e32 v36, 0, v36
	v_max_f32_e32 v37, 0, v37
	v_max_f32_e32 v38, 0, v38
	v_max_f32_e32 v39, 0, v39
	v_max_f32_e32 v32, 0, v32
	v_max_f32_e32 v33, 0, v33
; __device__ __forceinline__ unsigned cvt_pk_bf16(float lo, float hi) { unsigned r; asm volatile("v_cvt_pk_bf16_f32 %0, %1, %2" : "=v"(r) : "v"(lo), "v"(hi)); return r; }
;     __device__ __forceinline__ void operator()(const f32x4 (&acc)[2][2][4][2], const Unit& u, int wr, int wc, int fr, int fq) const {
;     ...
;         for (int ai = 0; ai < 2; ++ai)
; #pragma unroll
;             for (int m = 0; m < 4; ++m) { const int row = row0 + ai * HALF + m * 16; bf16_t* rowp = O + (size_t)row * ldc + col0; float s = 0.f, q = 0.f;
;                 const float rstd = rsv[ai][m];
; #pragma unroll
;                 for (int bj = 0; bj < 2; ++bj) { f32x4 v0 = acc[ai][bj][m][0] * rstd + bv[bj][0], v1 = acc[ai][bj][m][1] * rstd + bv[bj][1];
;                     if (ACT == 1) {
; #pragma unroll
;                         for (int e = 0; e < 4; ++e) { const float a = fmaxf(v0[e], 0.f), b2 = fmaxf(v1[e], 0.f); v0[e] = a * a; v1[e] = b2 * b2; } }
;                     if (ACT == 2) {
; #pragma unroll
;                         for (int e = 0; e < 4; ++e) { v0[e] = gelu_tanh(v0[e]); v1[e] = gelu_tanh(v1[e]); s += v0[e] + v1[e]; q += v0[e] * v0[e] + v1[e] * v1[e]; } }
;                     u32x4 w; w.x = cvt_pk_bf16(v0[0], v0[1]); w.y = cvt_pk_bf16(v0[2], v0[3]); w.z = cvt_pk_bf16(v1[0], v1[1]); w.w = cvt_pk_bf16(v1[2], v1[3]);
;                     *(u32x4*)(rowp + bj * HALF) = w; }
	v_max_f32_e32 v34, 0, v34
	v_max_f32_e32 v35, 0, v35
	v_pk_mul_f32 v[36:37], v[36:37], v[36:37]
	v_pk_mul_f32 v[38:39], v[38:39], v[38:39]
	v_pk_mul_f32 v[32:33], v[32:33], v[32:33]
	v_pk_mul_f32 v[34:35], v[34:35], v[34:35]
	v_cvt_pk_bf16_f32 v164, v36, v37
	v_cvt_pk_bf16_f32 v165, v38, v39
	v_cvt_pk_bf16_f32 v166, v32, v33
	v_cvt_pk_bf16_f32 v167, v34, v35
	global_store_dwordx4 v[208:209], v[164:167], off offset:256 sc1
	v_pk_fma_f32 v[28:29], v[28:29], v[156:157], v[128:129] op_sel_hi:[1,0,1]
	v_pk_fma_f32 v[30:31], v[30:31], v[156:157], v[130:131] op_sel_hi:[1,0,1]
	v_pk_fma_f32 v[24:25], v[24:25], v[156:157], v[132:133] op_sel_hi:[1,0,1]
	v_pk_fma_f32 v[26:27], v[26:27], v[156:157], v[134:135] op_sel_hi:[1,0,1]
	v_lshl_add_u64 v[208:209], v[208:209], 0, s[44:45]
	v_max_f32_e32 v28, 0, v28
	v_max_f32_e32 v29, 0, v29
	v_max_f32_e32 v30, 0, v30
	v_max_f32_e32 v31, 0, v31
	v_max_f32_e32 v24, 0, v24
	v_max_f32_e32 v25, 0, v25
	v_max_f32_e32 v26, 0, v26
	v_max_f32_e32 v27, 0, v27
	v_pk_mul_f32 v[28:29], v[28:29], v[28:29]
	v_pk_mul_f32 v[30:31], v[30:31], v[30:31]
	v_pk_mul_f32 v[24:25], v[24:25], v[24:25]
	v_pk_mul_f32 v[26:27], v[26:27], v[26:27]
	v_cvt_pk_bf16_f32 v160, v28, v29
	v_cvt_pk_bf16_f32 v161, v30, v31
	v_cvt_pk_bf16_f32 v162, v24, v25
	v_cvt_pk_bf16_f32 v163, v26, v27
	global_store_dwordx4 v[208:209], v[160:163], off sc1
	v_pk_fma_f32 v[20:21], v[20:21], v[156:157], v[136:137] op_sel_hi:[1,0,1]
	v_pk_fma_f32 v[22:23], v[22:23], v[156:157], v[138:139] op_sel_hi:[1,0,1]
	v_pk_fma_f32 v[16:17], v[16:17], v[156:157], v[140:141] op_sel_hi:[1,0,1]
	v_pk_fma_f32 v[18:19], v[18:19], v[156:157], v[142:143] op_sel_hi:[1,0,1]
	v_max_f32_e32 v20, 0, v20
	v_max_f32_e32 v21, 0, v21
	v_max_f32_e32 v22, 0, v22
	v_max_f32_e32 v23, 0, v23
	v_max_f32_e32 v16, 0, v16
	v_max_f32_e32 v17, 0, v17
	v_max_f32_e32 v18, 0, v18
	v_max_f32_e32 v19, 0, v19
	v_pk_mul_f32 v[20:21], v[20:21], v[20:21]
	v_pk_mul_f32 v[22:23], v[22:23], v[22:23]
	v_pk_mul_f32 v[16:17], v[16:17], v[16:17]
	v_pk_mul_f32 v[18:19], v[18:19], v[18:19]
	v_cvt_pk_bf16_f32 v164, v20, v21
	v_cvt_pk_bf16_f32 v165, v22, v23
	v_cvt_pk_bf16_f32 v166, v16, v17
	v_cvt_pk_bf16_f32 v167, v18, v19
	global_store_dwordx4 v[208:209], v[164:167], off offset:256 sc1
	v_pk_fma_f32 v[12:13], v[12:13], v[158:159], v[128:129] op_sel_hi:[1,0,1]
	v_pk_fma_f32 v[14:15], v[14:15], v[158:159], v[130:131] op_sel_hi:[1,0,1]
	v_pk_fma_f32 v[8:9], v[8:9], v[158:159], v[132:133] op_sel_hi:[1,0,1]
	v_pk_fma_f32 v[10:11], v[10:11], v[158:159], v[134:135] op_sel_hi:[1,0,1]
	v_lshl_add_u64 v[208:209], v[208:209], 0, s[44:45]
	v_max_f32_e32 v12, 0, v12
	v_max_f32_e32 v13, 0, v13
	v_max_f32_e32 v14, 0, v14
	v_max_f32_e32 v15, 0, v15
	v_max_f32_e32 v8, 0, v8
	v_max_f32_e32 v9, 0, v9
	v_max_f32_e32 v10, 0, v10
	v_max_f32_e32 v11, 0, v11
	v_pk_mul_f32 v[12:13], v[12:13], v[12:13]
	v_pk_mul_f32 v[14:15], v[14:15], v[14:15]
	v_pk_mul_f32 v[8:9], v[8:9], v[8:9]
	v_pk_mul_f32 v[10:11], v[10:11], v[10:11]
	v_cvt_pk_bf16_f32 v160, v12, v13
	v_cvt_pk_bf16_f32 v161, v14, v15
	v_cvt_pk_bf16_f32 v162, v8, v9
	v_cvt_pk_bf16_f32 v163, v10, v11
	global_store_dwordx4 v[208:209], v[160:163], off sc1
	v_pk_fma_f32 v[4:5], v[4:5], v[158:159], v[136:137] op_sel_hi:[1,0,1]
	v_pk_fma_f32 v[6:7], v[6:7], v[158:159], v[138:139] op_sel_hi:[1,0,1]
	v_pk_fma_f32 v[0:1], v[0:1], v[158:159], v[140:141] op_sel_hi:[1,0,1]
	v_pk_fma_f32 v[2:3], v[2:3], v[158:159], v[142:143] op_sel_hi:[1,0,1]
	v_max_f32_e32 v4, 0, v4
	v_max_f32_e32 v5, 0, v5
	v_max_f32_e32 v6, 0, v6
	v_max_f32_e32 v7, 0, v7
	v_max_f32_e32 v0, 0, v0
	v_max_f32_e32 v1, 0, v1
	v_max_f32_e32 v2, 0, v2
	v_max_f32_e32 v3, 0, v3
	v_pk_mul_f32 v[4:5], v[4:5], v[4:5]
	v_pk_mul_f32 v[6:7], v[6:7], v[6:7]
	v_pk_mul_f32 v[0:1], v[0:1], v[0:1]
	v_pk_mul_f32 v[2:3], v[2:3], v[2:3]
	v_cvt_pk_bf16_f32 v164, v4, v5
	v_cvt_pk_bf16_f32 v165, v6, v7
	v_cvt_pk_bf16_f32 v166, v0, v1
	v_cvt_pk_bf16_f32 v167, v2, v3
	global_store_dwordx4 v[208:209], v[164:167], off offset:256 sc1
	s_mov_b64 s[40:41], -1
	s_andn2_b64 vcc, exec, s[38:39]
	s_cbranch_vccnz .LBB0_1689
	s_andn2_b64 vcc, exec, s[12:13]
	s_cbranch_vccnz .LBB0_1688
	s_barrier
	s_branch .LBB0_1688
